# nt hint on the final-norm phase's output stores (never re-read)
# baseline (speedup 1.0000x reference)
; __device__ __forceinline__ float bflo(unsigned u) { return __uint_as_float(u << 16); }
; __device__ __forceinline__ float bfhi(unsigned u) { return __uint_as_float(u & 0xffff0000u); }
; __device__ void ph_final(const P& p) {
;     ...
;   for (int it = blockIdx.x; it < TT / 16; it += gridDim.x) {
;     const int t0 = it * 16 + wid * 4;
;     uint2 hb[4][4];
; #pragma unroll
;     for (int r = 0; r < 4; ++r)
; #pragma unroll
;       for (int i = 0; i < 4; ++i) hb[r][i] = *(const uint2*)(p_h16 + (size_t)(t0 + r) * DM + i * 256 + lane * 4);
; #pragma unroll
;     for (int r = 0; r < 4; ++r) {
;       f32x4 v[4];
;       float ss = 0.f;
; #pragma unroll
;       for (int i = 0; i < 4; ++i) {
;         v[i] = f32x4{bflo(hb[r][i].x), bfhi(hb[r][i].x), bflo(hb[r][i].y), bfhi(hb[r][i].y)};
;         ss += v[i][0] * v[i][0] + v[i][1] * v[i][1] + v[i][2] * v[i][2] + v[i][3] * v[i][3];
;       }
;       ss = wave_sum(ss);
;       const float rs = rsqrtf(ss * (1.f / 1024.f) + EPS);
; #pragma unroll
;       for (int i = 0; i < 4; ++i) *(f32x4*)(p.out + (size_t)(t0 + r) * DM + i * 256 + lane * 4) = v[i] * rs * g[i];
.LBB0_1174:
	v_ashrrev_i32_e32 v21, 31, v20
	v_lshlrev_b64 v[24:25], 11, v[20:21]
	v_add_u32_e32 v36, 1, v20
	v_lshl_add_u64 v[24:25], v[16:17], 0, v[24:25]
	v_ashrrev_i32_e32 v37, 31, v36
	global_load_dwordx2 v[38:39], v[24:25], off
	global_load_dwordx2 v[40:41], v[24:25], off offset:512
	global_load_dwordx2 v[42:43], v[24:25], off offset:1024
	global_load_dwordx2 v[44:45], v[24:25], off offset:1536
	v_lshlrev_b64 v[24:25], 11, v[36:37]
	v_lshl_add_u64 v[28:29], v[16:17], 0, v[24:25]
	global_load_dwordx2 v[46:47], v[28:29], off
	global_load_dwordx2 v[48:49], v[28:29], off offset:512
	global_load_dwordx2 v[50:51], v[28:29], off offset:1024
	global_load_dwordx2 v[52:53], v[28:29], off offset:1536
	v_add_u32_e32 v26, 2, v20
	v_add_u32_e32 v24, 3, v20
	v_ashrrev_i32_e32 v27, 31, v26
	v_ashrrev_i32_e32 v25, 31, v24
	v_lshlrev_b64 v[30:31], 11, v[26:27]
	v_lshlrev_b64 v[28:29], 11, v[24:25]
	v_lshl_add_u64 v[54:55], v[16:17], 0, v[30:31]
	v_lshl_add_u64 v[56:57], v[16:17], 0, v[28:29]
	global_load_dwordx2 v[34:35], v[54:55], off
	global_load_dwordx2 v[32:33], v[54:55], off offset:512
	global_load_dwordx2 v[30:31], v[54:55], off offset:1024
	global_load_dwordx2 v[28:29], v[54:55], off offset:1536
	v_lshlrev_b64 v[26:27], 12, v[26:27]
	s_add_i32 s10, s10, s8
	s_cmpk_lt_i32 s10, 0x840
	s_waitcnt vmcnt(11)
	v_and_b32_e32 v55, 0xffff0000, v38
	s_waitcnt vmcnt(10)
	v_and_b32_e32 v59, 0xffff0000, v40
	v_lshlrev_b32_e32 v54, 16, v38
	v_lshlrev_b32_e32 v58, 16, v40
	v_lshlrev_b32_e32 v60, 16, v41
	v_and_b32_e32 v61, 0xffff0000, v41
	s_waitcnt vmcnt(9)
	v_and_b32_e32 v63, 0xffff0000, v42
	v_mul_f32_e32 v40, v55, v55
	v_mul_f32_e32 v41, v59, v59
	v_lshlrev_b32_e32 v38, 16, v39
	v_lshlrev_b32_e32 v62, 16, v42
	s_waitcnt vmcnt(8)
	v_and_b32_e32 v65, 0xffff0000, v44
	v_mul_f32_e32 v72, v63, v63
	s_waitcnt vmcnt(7)
	v_and_b32_e32 v67, 0xffff0000, v46
	s_waitcnt vmcnt(6)
	v_and_b32_e32 v69, 0xffff0000, v48
	v_fmac_f32_e32 v40, v54, v54
	v_fmac_f32_e32 v41, v58, v58
	v_and_b32_e32 v39, 0xffff0000, v39
	v_lshlrev_b32_e32 v42, 16, v43
	v_lshlrev_b32_e32 v64, 16, v44
	v_mul_f32_e32 v73, v65, v65
	v_lshlrev_b32_e32 v66, 16, v46
	v_lshlrev_b32_e32 v68, 16, v48
	s_waitcnt vmcnt(5)
	v_and_b32_e32 v71, 0xffff0000, v50
	v_fmac_f32_e32 v72, v62, v62
	v_mul_f32_e32 v74, v67, v67
	v_mul_f32_e32 v75, v69, v69
	v_fmac_f32_e32 v40, v38, v38
	v_fmac_f32_e32 v41, v60, v60
	v_and_b32_e32 v43, 0xffff0000, v43
	v_lshlrev_b32_e32 v44, 16, v45
	v_lshlrev_b32_e32 v46, 16, v47
	v_lshlrev_b32_e32 v48, 16, v49
	v_lshlrev_b32_e32 v70, 16, v50
	v_fmac_f32_e32 v73, v64, v64
	v_mul_f32_e32 v76, v71, v71
	v_fmac_f32_e32 v72, v42, v42
	v_fmac_f32_e32 v74, v66, v66
	v_fmac_f32_e32 v75, v68, v68
	v_fmac_f32_e32 v40, v39, v39
	v_fmac_f32_e32 v41, v61, v61
	v_and_b32_e32 v45, 0xffff0000, v45
	v_and_b32_e32 v47, 0xffff0000, v47
	v_and_b32_e32 v49, 0xffff0000, v49
	v_lshlrev_b32_e32 v50, 16, v51
	v_fmac_f32_e32 v73, v44, v44
	v_fmac_f32_e32 v76, v70, v70
	v_fmac_f32_e32 v72, v43, v43
	v_fmac_f32_e32 v74, v46, v46
	v_fmac_f32_e32 v75, v48, v48
	v_add_f32_e32 v40, v40, v41
	v_and_b32_e32 v51, 0xffff0000, v51
	v_fmac_f32_e32 v73, v45, v45
	v_fmac_f32_e32 v76, v50, v50
	v_fmac_f32_e32 v74, v47, v47
	v_fmac_f32_e32 v75, v49, v49
	v_add_f32_e32 v40, v40, v72
	v_fmac_f32_e32 v76, v51, v51
	v_add_f32_e32 v72, v74, v75
	v_add_f32_e32 v40, v40, v73
	s_waitcnt vmcnt(4)
	v_and_b32_e32 v73, 0xffff0000, v52
	v_add_f32_e32 v74, v72, v76
	v_lshlrev_b32_e32 v72, 16, v52
	v_mul_f32_e32 v75, v73, v73
	v_lshlrev_b32_e32 v52, 16, v53
	v_fmac_f32_e32 v75, v72, v72
	v_and_b32_e32 v53, 0xffff0000, v53
	v_fmac_f32_e32 v75, v52, v52
	v_fmac_f32_e32 v75, v53, v53
	v_add_f32_dpp v40, v40, v40 quad_perm:[1,0,3,2] row_mask:0xf bank_mask:0xf bound_ctrl:1
	v_add_f32_e32 v74, v74, v75
	s_nop 0
	v_add_f32_dpp v40, v40, v40 quad_perm:[2,3,0,1] row_mask:0xf bank_mask:0xf bound_ctrl:1
	v_add_f32_dpp v74, v74, v74 quad_perm:[1,0,3,2] row_mask:0xf bank_mask:0xf bound_ctrl:1
	s_nop 0
	v_add_f32_dpp v40, v40, v40 row_half_mirror row_mask:0xf bank_mask:0xf bound_ctrl:1
	v_add_f32_dpp v74, v74, v74 quad_perm:[2,3,0,1] row_mask:0xf bank_mask:0xf bound_ctrl:1
	s_nop 0
	v_add_f32_dpp v40, v40, v40 row_mirror row_mask:0xf bank_mask:0xf bound_ctrl:1
	v_add_f32_dpp v74, v74, v74 row_half_mirror row_mask:0xf bank_mask:0xf bound_ctrl:1
	v_readlane_b32 s3, v40, 16
	v_readlane_b32 s6, v40, 48
	v_add_f32_dpp v74, v74, v74 row_mirror row_mask:0xf bank_mask:0xf bound_ctrl:1
	v_readlane_b32 s4, v40, 0
	v_readlane_b32 s5, v40, 32
	v_mov_b32_e32 v40, s3
	v_mov_b32_e32 v41, s6
	v_readlane_b32 s3, v74, 16
	v_readlane_b32 s6, v74, 48
	v_pk_add_f32 v[40:41], s[4:5], v[40:41]
	v_readlane_b32 s4, v74, 0
	v_readlane_b32 s5, v74, 32
	v_mov_b32_e32 v74, s3
	v_mov_b32_e32 v75, s6
	v_pk_add_f32 v[74:75], s[4:5], v[74:75]
	v_mov_b32_e32 v77, v40
	v_mov_b32_e32 v76, v74
	v_mov_b32_e32 v40, v75
	v_pk_add_f32 v[40:41], v[76:77], v[40:41]
	global_load_dwordx2 v[76:77], v[56:57], off
	global_load_dwordx2 v[78:79], v[56:57], off offset:512
	global_load_dwordx2 v[80:81], v[56:57], off offset:1024
	global_load_dwordx2 v[82:83], v[56:57], off offset:1536
	v_pk_fma_f32 v[74:75], v[40:41], s[0:1], v[22:23] op_sel_hi:[1,0,0]
	s_nop 0
	v_mul_f32_e32 v40, 0x4b800000, v75
	v_cmp_gt_f32_e32 vcc, s2, v75
	s_nop 1
	v_cndmask_b32_e32 v40, v75, v40, vcc
	v_rsq_f32_e32 v75, v40
	v_lshlrev_b64 v[40:41], 12, v[20:21]
	v_lshl_add_u64 v[56:57], v[18:19], 0, v[40:41]
	v_add_u32_e32 v20, s1, v20
	v_mul_f32_e32 v21, 0x45800000, v75
	v_cndmask_b32_e32 v84, v75, v21, vcc
	v_pk_mul_f32 v[54:55], v[54:55], v[84:85] op_sel_hi:[1,0]
	v_pk_mul_f32 v[38:39], v[38:39], v[84:85] op_sel_hi:[1,0]
	v_mul_f32_e32 v21, 0x4b800000, v74
	v_pk_mul_f32 v[40:41], v[2:3], v[38:39]
	v_pk_mul_f32 v[38:39], v[0:1], v[54:55]
	global_store_dwordx4 v[56:57], v[38:41], off nt
	v_cmp_gt_f32_e32 vcc, s2, v74
	s_waitcnt vmcnt(4)
; __device__ __forceinline__ float bflo(unsigned u) { return __uint_as_float(u << 16); }
; __device__ __forceinline__ float bfhi(unsigned u) { return __uint_as_float(u & 0xffff0000u); }
; __device__ void ph_final(const P& p) {
;     ...
;   for (int it = blockIdx.x; it < TT / 16; it += gridDim.x) {
;     const int t0 = it * 16 + wid * 4;
;     uint2 hb[4][4];
; #pragma unroll
;     for (int r = 0; r < 4; ++r)
; #pragma unroll
;       for (int i = 0; i < 4; ++i) hb[r][i] = *(const uint2*)(p_h16 + (size_t)(t0 + r) * DM + i * 256 + lane * 4);
; #pragma unroll
;     for (int r = 0; r < 4; ++r) {
;       f32x4 v[4];
;       float ss = 0.f;
; #pragma unroll
;       for (int i = 0; i < 4; ++i) {
;         v[i] = f32x4{bflo(hb[r][i].x), bfhi(hb[r][i].x), bflo(hb[r][i].y), bfhi(hb[r][i].y)};
;         ss += v[i][0] * v[i][0] + v[i][1] * v[i][1] + v[i][2] * v[i][2] + v[i][3] * v[i][3];
;       }
;       ss = wave_sum(ss);
;       const float rs = rsqrtf(ss * (1.f / 1024.f) + EPS);
; #pragma unroll
;       for (int i = 0; i < 4; ++i) *(f32x4*)(p.out + (size_t)(t0 + r) * DM + i * 256 + lane * 4) = v[i] * rs * g[i];
	v_lshlrev_b32_e32 v54, 16, v77
	v_pk_mul_f32 v[38:39], v[58:59], v[84:85] op_sel_hi:[1,0]
	v_pk_mul_f32 v[40:41], v[60:61], v[84:85] op_sel_hi:[1,0]
	v_pk_mul_f32 v[38:39], v[4:5], v[38:39]
	v_pk_mul_f32 v[40:41], v[6:7], v[40:41]
	v_cndmask_b32_e32 v21, v74, v21, vcc
	global_store_dwordx4 v[56:57], v[38:41], off offset:1024 nt
	v_rsq_f32_e32 v21, v21
	s_waitcnt vmcnt(4)
	v_lshlrev_b32_e32 v58, 16, v79
	v_pk_mul_f32 v[38:39], v[62:63], v[84:85] op_sel_hi:[1,0]
	v_pk_mul_f32 v[40:41], v[42:43], v[84:85] op_sel_hi:[1,0]
	v_pk_mul_f32 v[38:39], v[8:9], v[38:39]
	v_pk_mul_f32 v[40:41], v[10:11], v[40:41]
	global_store_dwordx4 v[56:57], v[38:41], off offset:2048 nt
	v_lshlrev_b64 v[42:43], 12, v[36:37]
	v_lshl_add_u64 v[42:43], v[18:19], 0, v[42:43]
	v_pk_mul_f32 v[38:39], v[64:65], v[84:85] op_sel_hi:[1,0]
	v_pk_mul_f32 v[40:41], v[44:45], v[84:85] op_sel_hi:[1,0]
	v_pk_mul_f32 v[38:39], v[12:13], v[38:39]
	v_pk_mul_f32 v[40:41], v[14:15], v[40:41]
	global_store_dwordx4 v[56:57], v[38:41], off offset:3072 nt
	v_and_b32_e32 v45, 0xffff0000, v32
	v_lshlrev_b32_e32 v44, 16, v32
	v_mul_f32_e32 v38, 0x45800000, v21
	v_cndmask_b32_e32 v40, v21, v38, vcc
	v_pk_mul_f32 v[36:37], v[66:67], v[40:41] op_sel_hi:[1,0]
	v_pk_mul_f32 v[38:39], v[46:47], v[40:41] op_sel_hi:[1,0]
	v_pk_mul_f32 v[36:37], v[0:1], v[36:37]
	v_pk_mul_f32 v[38:39], v[2:3], v[38:39]
	global_store_dwordx4 v[42:43], v[36:39], off nt
	v_mul_f32_e32 v46, v45, v45
	v_lshlrev_b32_e32 v32, 16, v33
	v_pk_mul_f32 v[36:37], v[68:69], v[40:41] op_sel_hi:[1,0]
	v_pk_mul_f32 v[38:39], v[48:49], v[40:41] op_sel_hi:[1,0]
	v_pk_mul_f32 v[36:37], v[4:5], v[36:37]
	v_pk_mul_f32 v[38:39], v[6:7], v[38:39]
	global_store_dwordx4 v[42:43], v[36:39], off offset:1024 nt
	v_fmac_f32_e32 v46, v44, v44
	v_and_b32_e32 v33, 0xffff0000, v33
	v_pk_mul_f32 v[36:37], v[70:71], v[40:41] op_sel_hi:[1,0]
	v_pk_mul_f32 v[38:39], v[50:51], v[40:41] op_sel_hi:[1,0]
	v_pk_mul_f32 v[36:37], v[8:9], v[36:37]
	v_pk_mul_f32 v[38:39], v[10:11], v[38:39]
	global_store_dwordx4 v[42:43], v[36:39], off offset:2048 nt
	v_fmac_f32_e32 v46, v32, v32
	v_fmac_f32_e32 v46, v33, v33
	v_pk_mul_f32 v[36:37], v[72:73], v[40:41] op_sel_hi:[1,0]
	v_pk_mul_f32 v[38:39], v[52:53], v[40:41] op_sel_hi:[1,0]
	v_and_b32_e32 v41, 0xffff0000, v34
	v_lshlrev_b32_e32 v40, 16, v34
	v_mul_f32_e32 v21, v41, v41
	v_lshlrev_b32_e32 v34, 16, v35
	v_fmac_f32_e32 v21, v40, v40
	v_and_b32_e32 v35, 0xffff0000, v35
	v_fmac_f32_e32 v21, v34, v34
	v_fmac_f32_e32 v21, v35, v35
	v_and_b32_e32 v47, 0xffff0000, v30
	v_add_f32_e32 v21, v21, v46
	v_lshlrev_b32_e32 v46, 16, v30
	v_mul_f32_e32 v48, v47, v47
	v_lshlrev_b32_e32 v30, 16, v31
	v_fmac_f32_e32 v48, v46, v46
	v_and_b32_e32 v31, 0xffff0000, v31
	v_fmac_f32_e32 v48, v30, v30
	v_fmac_f32_e32 v48, v31, v31
	v_and_b32_e32 v49, 0xffff0000, v28
	v_add_f32_e32 v21, v21, v48
	v_lshlrev_b32_e32 v48, 16, v28
	v_mul_f32_e32 v28, v49, v49
	v_lshlrev_b32_e32 v50, 16, v29
	v_fmac_f32_e32 v28, v48, v48
	v_and_b32_e32 v51, 0xffff0000, v29
	v_fmac_f32_e32 v28, v50, v50
	v_fmac_f32_e32 v28, v51, v51
	v_add_f32_e32 v21, v21, v28
	v_and_b32_e32 v53, 0xffff0000, v76
	v_and_b32_e32 v57, 0xffff0000, v78
	v_add_f32_dpp v21, v21, v21 quad_perm:[1,0,3,2] row_mask:0xf bank_mask:0xf bound_ctrl:1
	v_lshlrev_b32_e32 v52, 16, v76
	v_lshlrev_b32_e32 v56, 16, v78
	v_add_f32_dpp v21, v21, v21 quad_perm:[2,3,0,1] row_mask:0xf bank_mask:0xf bound_ctrl:1
	v_mul_f32_e32 v60, v57, v57
	v_fmac_f32_e32 v60, v56, v56
	v_add_f32_dpp v21, v21, v21 row_half_mirror row_mask:0xf bank_mask:0xf bound_ctrl:1
	v_and_b32_e32 v55, 0xffff0000, v77
	v_and_b32_e32 v59, 0xffff0000, v79
	v_add_f32_dpp v21, v21, v21 row_mirror row_mask:0xf bank_mask:0xf bound_ctrl:1
	v_fmac_f32_e32 v60, v58, v58
	v_readlane_b32 s4, v21, 0
	v_readlane_b32 s3, v21, 16
	v_readlane_b32 s5, v21, 32
	v_readlane_b32 s6, v21, 48
	v_mul_f32_e32 v21, v53, v53
	v_fmac_f32_e32 v21, v52, v52
	v_fmac_f32_e32 v21, v54, v54
	v_fmac_f32_e32 v21, v55, v55
	v_fmac_f32_e32 v60, v59, v59
	s_waitcnt vmcnt(8)
; __device__ __forceinline__ float bflo(unsigned u) { return __uint_as_float(u << 16); }
; __device__ __forceinline__ float bfhi(unsigned u) { return __uint_as_float(u & 0xffff0000u); }
; __device__ void ph_final(const P& p) {
;     ...
;   for (int it = blockIdx.x; it < TT / 16; it += gridDim.x) {
;     const int t0 = it * 16 + wid * 4;
;     uint2 hb[4][4];
; #pragma unroll
;     for (int r = 0; r < 4; ++r)
; #pragma unroll
;       for (int i = 0; i < 4; ++i) hb[r][i] = *(const uint2*)(p_h16 + (size_t)(t0 + r) * DM + i * 256 + lane * 4);
; #pragma unroll
;     for (int r = 0; r < 4; ++r) {
;       f32x4 v[4];
;       float ss = 0.f;
; #pragma unroll
;       for (int i = 0; i < 4; ++i) {
;         v[i] = f32x4{bflo(hb[r][i].x), bfhi(hb[r][i].x), bflo(hb[r][i].y), bfhi(hb[r][i].y)};
;         ss += v[i][0] * v[i][0] + v[i][1] * v[i][1] + v[i][2] * v[i][2] + v[i][3] * v[i][3];
;       }
;       ss = wave_sum(ss);
;       const float rs = rsqrtf(ss * (1.f / 1024.f) + EPS);
; #pragma unroll
;       for (int i = 0; i < 4; ++i) *(f32x4*)(p.out + (size_t)(t0 + r) * DM + i * 256 + lane * 4) = v[i] * rs * g[i];
	v_and_b32_e32 v61, 0xffff0000, v80
	v_add_f32_e32 v21, v21, v60
	v_lshlrev_b32_e32 v60, 16, v80
	v_mul_f32_e32 v64, v61, v61
	v_lshlrev_b32_e32 v62, 16, v81
	v_fmac_f32_e32 v64, v60, v60
	v_and_b32_e32 v63, 0xffff0000, v81
	v_fmac_f32_e32 v64, v62, v62
	v_fmac_f32_e32 v64, v63, v63
	s_waitcnt vmcnt(7)
	v_and_b32_e32 v65, 0xffff0000, v82
	v_add_f32_e32 v21, v21, v64
	v_lshlrev_b32_e32 v64, 16, v82
	v_mul_f32_e32 v68, v65, v65
	v_lshlrev_b32_e32 v66, 16, v83
	v_fmac_f32_e32 v68, v64, v64
	v_and_b32_e32 v67, 0xffff0000, v83
	v_fmac_f32_e32 v68, v66, v66
	v_fmac_f32_e32 v68, v67, v67
	v_add_f32_e32 v21, v21, v68
	v_mov_b32_e32 v28, s3
	v_mov_b32_e32 v29, s6
	v_add_f32_dpp v21, v21, v21 quad_perm:[1,0,3,2] row_mask:0xf bank_mask:0xf bound_ctrl:1
	v_pk_add_f32 v[28:29], s[4:5], v[28:29]
	v_pk_mul_f32 v[38:39], v[14:15], v[38:39]
	v_add_f32_dpp v21, v21, v21 quad_perm:[2,3,0,1] row_mask:0xf bank_mask:0xf bound_ctrl:1
	v_mov_b32_e32 v71, v28
	v_pk_mul_f32 v[36:37], v[12:13], v[36:37]
	v_add_f32_dpp v21, v21, v21 row_half_mirror row_mask:0xf bank_mask:0xf bound_ctrl:1
	global_store_dwordx4 v[42:43], v[36:39], off offset:3072 nt
	s_nop 0
	v_add_f32_dpp v21, v21, v21 row_mirror row_mask:0xf bank_mask:0xf bound_ctrl:1
	v_lshl_add_u64 v[36:37], v[18:19], 0, v[26:27]
	v_readlane_b32 s3, v21, 16
	v_readlane_b32 s6, v21, 48
	v_readlane_b32 s4, v21, 0
	v_readlane_b32 s5, v21, 32
	v_mov_b32_e32 v68, s3
	v_mov_b32_e32 v69, s6
	v_pk_add_f32 v[68:69], s[4:5], v[68:69]
	s_nop 0
	v_mov_b32_e32 v70, v68
	v_mov_b32_e32 v28, v69
	v_pk_add_f32 v[28:29], v[70:71], v[28:29]
	s_nop 0
	v_pk_fma_f32 v[68:69], v[28:29], s[0:1], v[22:23] op_sel_hi:[1,0,0]
	s_nop 0
	v_mul_f32_e32 v21, 0x4b800000, v69
	v_cmp_gt_f32_e32 vcc, s2, v69
	s_nop 1
	v_cndmask_b32_e32 v21, v69, v21, vcc
	v_rsq_f32_e32 v21, v21
	s_nop 0
	v_mul_f32_e32 v26, 0x45800000, v21
	v_cndmask_b32_e32 v38, v21, v26, vcc
	v_pk_mul_f32 v[26:27], v[40:41], v[38:39] op_sel_hi:[1,0]
	v_pk_mul_f32 v[28:29], v[34:35], v[38:39] op_sel_hi:[1,0]
	v_pk_mul_f32 v[26:27], v[0:1], v[26:27]
	v_pk_mul_f32 v[28:29], v[2:3], v[28:29]
	global_store_dwordx4 v[36:37], v[26:29], off nt
	v_mul_f32_e32 v21, 0x4b800000, v68
	v_cmp_gt_f32_e32 vcc, s2, v68
	v_pk_mul_f32 v[26:27], v[44:45], v[38:39] op_sel_hi:[1,0]
	v_pk_mul_f32 v[28:29], v[32:33], v[38:39] op_sel_hi:[1,0]
	v_pk_mul_f32 v[26:27], v[4:5], v[26:27]
	v_pk_mul_f32 v[28:29], v[6:7], v[28:29]
	v_cndmask_b32_e32 v21, v68, v21, vcc
	global_store_dwordx4 v[36:37], v[26:29], off offset:1024 nt
	v_rsq_f32_e32 v21, v21
	s_nop 0
	v_pk_mul_f32 v[26:27], v[46:47], v[38:39] op_sel_hi:[1,0]
	v_pk_mul_f32 v[28:29], v[30:31], v[38:39] op_sel_hi:[1,0]
	v_pk_mul_f32 v[26:27], v[8:9], v[26:27]
	v_pk_mul_f32 v[28:29], v[10:11], v[28:29]
	global_store_dwordx4 v[36:37], v[26:29], off offset:2048 nt
	v_lshlrev_b64 v[30:31], 12, v[24:25]
	v_lshl_add_u64 v[30:31], v[18:19], 0, v[30:31]
	v_pk_mul_f32 v[26:27], v[48:49], v[38:39] op_sel_hi:[1,0]
	v_pk_mul_f32 v[28:29], v[50:51], v[38:39] op_sel_hi:[1,0]
	v_pk_mul_f32 v[26:27], v[12:13], v[26:27]
	v_pk_mul_f32 v[28:29], v[14:15], v[28:29]
	global_store_dwordx4 v[36:37], v[26:29], off offset:3072 nt
	s_nop 1
	v_mul_f32_e32 v26, 0x45800000, v21
	v_cndmask_b32_e32 v28, v21, v26, vcc
	v_pk_mul_f32 v[24:25], v[52:53], v[28:29] op_sel_hi:[1,0]
	v_pk_mul_f32 v[26:27], v[54:55], v[28:29] op_sel_hi:[1,0]
	v_pk_mul_f32 v[24:25], v[0:1], v[24:25]
	v_pk_mul_f32 v[26:27], v[2:3], v[26:27]
	global_store_dwordx4 v[30:31], v[24:27], off nt
	s_nop 1
	v_pk_mul_f32 v[24:25], v[56:57], v[28:29] op_sel_hi:[1,0]
	v_pk_mul_f32 v[26:27], v[58:59], v[28:29] op_sel_hi:[1,0]
	v_pk_mul_f32 v[24:25], v[4:5], v[24:25]
	v_pk_mul_f32 v[26:27], v[6:7], v[26:27]
	global_store_dwordx4 v[30:31], v[24:27], off offset:1024 nt
	s_nop 1
	v_pk_mul_f32 v[24:25], v[60:61], v[28:29] op_sel_hi:[1,0]
	v_pk_mul_f32 v[26:27], v[62:63], v[28:29] op_sel_hi:[1,0]
	v_pk_mul_f32 v[24:25], v[8:9], v[24:25]
	v_pk_mul_f32 v[26:27], v[10:11], v[26:27]
	global_store_dwordx4 v[30:31], v[24:27], off offset:2048 nt
	s_nop 1
	v_pk_mul_f32 v[24:25], v[64:65], v[28:29] op_sel_hi:[1,0]
	v_pk_mul_f32 v[26:27], v[66:67], v[28:29] op_sel_hi:[1,0]
	v_pk_mul_f32 v[24:25], v[12:13], v[24:25]
	v_pk_mul_f32 v[26:27], v[14:15], v[26:27]
	global_store_dwordx4 v[30:31], v[24:27], off offset:3072 nt
	s_cbranch_scc1 .LBB0_1174
